# k17 + code touches before grid barriers 1 and 2 (barrier bodies and the following phase code warm in L2)
# speedup vs baseline: 1.0062x; 1.0062x over previous
.LBB0_94:
	s_getpc_b64 s[98:99]
	v_lshlrev_b32_e32 v246, 7, v202
	v_mov_b32_e32 v247, 0
	v_lshl_add_u64 v[246:247], v[246:247], 0, s[98:99]
	global_load_dword v248, v[246:247], off
	v_mov_b32_e32 v2, v202
	s_load_dwordx16 s[4:19], s[0:1], 0x0
	v_ashrrev_i32_e32 v0, 3, v2
	s_lshl_b32 s33, s96, 6
	v_and_b32_e32 v0, -8, v0
	v_add_u32_e32 v0, s33, v0
	v_ashrrev_i32_e32 v1, 31, v0
	v_lshlrev_b64 v[0:1], 12, v[0:1]
	v_lshlrev_b32_e32 v2, 4, v2
	s_waitcnt lgkmcnt(0)
	v_lshl_add_u64 v[0:1], s[4:5], 0, v[0:1]
	v_and_b32_e32 v2, 0x3f0, v2
	v_mov_b32_e32 v3, 0
	v_lshl_add_u64 v[0:1], v[0:1], 0, v[2:3]
	s_movk_i32 s2, 0x2000
	v_add_co_u32_e32 v2, vcc, s2, v0
	global_load_dwordx4 v[124:127], v[0:1], off
	s_nop 0
	v_addc_co_u32_e32 v3, vcc, 0, v1, vcc
	global_load_dwordx4 v[108:111], v[2:3], off offset:-4096
	global_load_dwordx4 v[112:115], v[0:1], off offset:1024
	s_movk_i32 s2, 0x1000
	v_add_co_u32_e32 v4, vcc, s2, v0
	s_movk_i32 s2, 0x3000
	s_nop 0
	v_addc_co_u32_e32 v5, vcc, 0, v1, vcc
	global_load_dwordx4 v[104:107], v[4:5], off offset:1024
	global_load_dwordx4 v[120:123], v[0:1], off offset:2048
	global_load_dwordx4 v[116:119], v[0:1], off offset:3072
	global_load_dwordx4 v[96:99], v[4:5], off offset:2048
	global_load_dwordx4 v[92:95], v[2:3], off
	global_load_dwordx4 v[84:87], v[2:3], off offset:1024
	global_load_dwordx4 v[76:79], v[2:3], off offset:2048
	global_load_dwordx4 v[64:67], v[2:3], off offset:3072
	v_add_co_u32_e32 v2, vcc, s2, v0
	s_movk_i32 s2, 0x4000
	s_nop 0
	v_addc_co_u32_e32 v3, vcc, 0, v1, vcc
	v_add_co_u32_e32 v72, vcc, s2, v0
	s_movk_i32 s2, 0x5000
	s_nop 0
	v_addc_co_u32_e32 v73, vcc, 0, v1, vcc
	global_load_dwordx4 v[100:103], v[4:5], off offset:3072
	global_load_dwordx4 v[60:63], v[2:3], off offset:1024
	global_load_dwordx4 v[56:59], v[2:3], off offset:2048
	global_load_dwordx4 v[52:55], v[2:3], off offset:3072
	global_load_dwordx4 v[68:71], v[72:73], off offset:-4096
	global_load_dwordx4 v[48:51], v[72:73], off
	global_load_dwordx4 v[44:47], v[72:73], off offset:1024
	global_load_dwordx4 v[40:43], v[72:73], off offset:2048
	v_add_co_u32_e32 v2, vcc, s2, v0
	s_movk_i32 s2, 0x6000
	s_nop 0
	v_addc_co_u32_e32 v3, vcc, 0, v1, vcc
	v_add_co_u32_e32 v74, vcc, s2, v0
	s_movk_i32 s2, 0x7000
	s_nop 0
	v_addc_co_u32_e32 v75, vcc, 0, v1, vcc
	global_load_dwordx4 v[36:39], v[72:73], off offset:3072
	global_load_dwordx4 v[32:35], v[74:75], off offset:-4096
	global_load_dwordx4 v[28:31], v[2:3], off offset:1024
	global_load_dwordx4 v[24:27], v[2:3], off offset:2048
	global_load_dwordx4 v[20:23], v[2:3], off offset:3072
	global_load_dwordx4 v[16:19], v[74:75], off
	global_load_dwordx4 v[12:15], v[74:75], off offset:1024
	global_load_dwordx4 v[8:11], v[74:75], off offset:2048
	global_load_dwordx4 v[4:7], v[74:75], off offset:3072
	v_mbcnt_lo_u32_b32 v74, -1, 0
	v_mbcnt_hi_u32_b32 v130, -1, v74
	v_add_co_u32_e32 v72, vcc, s2, v0
	v_and_b32_e32 v75, 64, v130
	s_nop 0
	v_addc_co_u32_e32 v73, vcc, 0, v1, vcc
	v_xor_b32_e32 v74, 1, v130
	v_add_u32_e32 v131, 64, v75
	v_cmp_lt_i32_e32 vcc, v74, v131
	v_xor_b32_e32 v90, 4, v130
	v_xor_b32_e32 v132, 32, v130
	v_cndmask_b32_e32 v74, v130, v74, vcc
	v_lshlrev_b32_e32 v203, 2, v74
	v_xor_b32_e32 v74, 2, v130
	v_cmp_lt_i32_e32 vcc, v74, v131
	global_load_dwordx4 v[0:3], v[72:73], off offset:3072
	s_mov_b32 s4, 0x358637bd
	v_cndmask_b32_e32 v74, v130, v74, vcc
	v_lshlrev_b32_e32 v204, 2, v74
	v_cmp_lt_i32_e32 vcc, v90, v131
	s_mov_b32 s2, 0x3a800000
	s_waitcnt vmcnt(28)
	v_mov_b32_e32 v80, v125
	v_mov_b32_e32 v74, v124
	s_waitcnt vmcnt(27)
	v_mov_b32_e32 v81, v109
	v_mov_b32_e32 v75, v108
	v_pk_mul_f32 v[80:81], v[80:81], v[80:81]
	v_mov_b32_e32 v82, v127
	v_mov_b32_e32 v83, v111
	v_pk_fma_f32 v[74:75], v[74:75], v[74:75], v[80:81]
	v_mov_b32_e32 v80, v126
	v_mov_b32_e32 v81, v110
	v_pk_mul_f32 v[82:83], v[82:83], v[82:83]
	s_waitcnt vmcnt(26)
	v_mov_b32_e32 v88, v115
	v_pk_fma_f32 v[80:81], v[80:81], v[80:81], v[82:83]
	v_mov_b32_e32 v82, v113
	s_waitcnt vmcnt(25)
	v_mov_b32_e32 v83, v105
	v_pk_add_f32 v[74:75], v[74:75], v[80:81]
	v_mov_b32_e32 v80, v112
	v_mov_b32_e32 v81, v104
	v_pk_mul_f32 v[82:83], v[82:83], v[82:83]
	v_mov_b32_e32 v89, v107
	v_pk_fma_f32 v[80:81], v[80:81], v[80:81], v[82:83]
	v_mov_b32_e32 v82, v114
	v_mov_b32_e32 v83, v106
	v_pk_mul_f32 v[88:89], v[88:89], v[88:89]
	s_waitcnt vmcnt(13)
	v_mov_b32_e32 v91, v71
	v_pk_fma_f32 v[82:83], v[82:83], v[82:83], v[88:89]
	v_mov_b32_e32 v88, v123
	v_pk_add_f32 v[80:81], v[80:81], v[82:83]
	v_mov_b32_e32 v82, v121
	v_mov_b32_e32 v83, v97
	v_pk_add_f32 v[74:75], v[74:75], v[80:81]
	v_mov_b32_e32 v80, v120
	v_mov_b32_e32 v81, v96
	v_pk_mul_f32 v[82:83], v[82:83], v[82:83]
	v_mov_b32_e32 v89, v99
	v_pk_fma_f32 v[80:81], v[80:81], v[80:81], v[82:83]
	v_mov_b32_e32 v82, v122
	v_mov_b32_e32 v83, v98
	v_pk_mul_f32 v[88:89], v[88:89], v[88:89]
	v_mov_b32_e32 v128, v87
	v_pk_fma_f32 v[82:83], v[82:83], v[82:83], v[88:89]
	v_mov_b32_e32 v88, v119
	v_pk_add_f32 v[80:81], v[80:81], v[82:83]
	v_mov_b32_e32 v82, v117
	v_mov_b32_e32 v83, v101
	v_pk_add_f32 v[74:75], v[74:75], v[80:81]
	v_mov_b32_e32 v80, v116
	v_mov_b32_e32 v81, v100
	v_pk_mul_f32 v[82:83], v[82:83], v[82:83]
	v_mov_b32_e32 v89, v103
	v_pk_fma_f32 v[80:81], v[80:81], v[80:81], v[82:83]
	v_mov_b32_e32 v82, v118
	v_mov_b32_e32 v83, v102
	v_pk_mul_f32 v[88:89], v[88:89], v[88:89]
	v_mov_b32_e32 v129, v63
	v_pk_fma_f32 v[82:83], v[82:83], v[82:83], v[88:89]
	v_mov_b32_e32 v88, v93
	v_pk_add_f32 v[80:81], v[80:81], v[82:83]
	v_cndmask_b32_e32 v82, v130, v90, vcc
	v_lshlrev_b32_e32 v205, 2, v82
	v_xor_b32_e32 v82, 8, v130
	v_cmp_lt_i32_e32 vcc, v82, v131
	v_pk_add_f32 v[74:75], v[74:75], v[80:81]
	ds_bpermute_b32 v80, v203, v74
	v_cndmask_b32_e32 v82, v130, v82, vcc
	v_lshlrev_b32_e32 v206, 2, v82
	v_xor_b32_e32 v82, 16, v130
	ds_bpermute_b32 v81, v203, v75
	v_cmp_lt_i32_e32 vcc, v82, v131
	v_mov_b32_e32 v89, v69
	v_mov_b32_e32 v83, v68
	v_cndmask_b32_e32 v82, v130, v82, vcc
	v_lshlrev_b32_e32 v207, 2, v82
	v_mov_b32_e32 v82, v92
	v_pk_mul_f32 v[88:89], v[88:89], v[88:89]
	v_mov_b32_e32 v90, v95
	v_pk_fma_f32 v[82:83], v[82:83], v[82:83], v[88:89]
	v_mov_b32_e32 v88, v94
	v_mov_b32_e32 v89, v70
	v_pk_mul_f32 v[90:91], v[90:91], v[90:91]
	s_waitcnt lgkmcnt(0)
	v_pk_add_f32 v[74:75], v[74:75], v[80:81]
	v_pk_fma_f32 v[88:89], v[88:89], v[88:89], v[90:91]
	v_mov_b32_e32 v90, v85
	v_mov_b32_e32 v91, v61
	v_pk_add_f32 v[82:83], v[82:83], v[88:89]
	v_mov_b32_e32 v88, v84
	v_mov_b32_e32 v89, v60
	v_pk_mul_f32 v[90:91], v[90:91], v[90:91]
	ds_bpermute_b32 v80, v204, v74
	ds_bpermute_b32 v81, v204, v75
	v_pk_fma_f32 v[88:89], v[88:89], v[88:89], v[90:91]
	v_mov_b32_e32 v90, v86
	v_mov_b32_e32 v91, v62
	v_pk_mul_f32 v[128:129], v[128:129], v[128:129]
	s_waitcnt lgkmcnt(0)
	v_pk_add_f32 v[74:75], v[74:75], v[80:81]
	v_pk_fma_f32 v[90:91], v[90:91], v[90:91], v[128:129]
	v_mov_b32_e32 v128, v79
	v_pk_add_f32 v[88:89], v[88:89], v[90:91]
	v_mov_b32_e32 v90, v77
	v_mov_b32_e32 v91, v57
	v_pk_add_f32 v[82:83], v[82:83], v[88:89]
	v_mov_b32_e32 v88, v76
	v_mov_b32_e32 v89, v56
	v_pk_mul_f32 v[90:91], v[90:91], v[90:91]
	v_mov_b32_e32 v129, v59
	v_pk_fma_f32 v[88:89], v[88:89], v[88:89], v[90:91]
	v_mov_b32_e32 v90, v78
	v_mov_b32_e32 v91, v58
	v_pk_mul_f32 v[128:129], v[128:129], v[128:129]
	ds_bpermute_b32 v80, v205, v74
	v_pk_fma_f32 v[90:91], v[90:91], v[90:91], v[128:129]
	ds_bpermute_b32 v81, v205, v75
	v_pk_add_f32 v[88:89], v[88:89], v[90:91]
	v_mov_b32_e32 v90, v65
	v_mov_b32_e32 v91, v53
	v_pk_add_f32 v[82:83], v[82:83], v[88:89]
	v_mov_b32_e32 v88, v64
	v_mov_b32_e32 v89, v52
	v_pk_mul_f32 v[90:91], v[90:91], v[90:91]
	v_mov_b32_e32 v128, v67
	v_mov_b32_e32 v129, v55
	v_pk_fma_f32 v[88:89], v[88:89], v[88:89], v[90:91]
	v_mov_b32_e32 v90, v66
	v_mov_b32_e32 v91, v54
	v_pk_mul_f32 v[128:129], v[128:129], v[128:129]
	s_waitcnt lgkmcnt(0)
	v_pk_add_f32 v[74:75], v[74:75], v[80:81]
	v_pk_fma_f32 v[90:91], v[90:91], v[90:91], v[128:129]
	ds_bpermute_b32 v80, v206, v74
	v_pk_add_f32 v[88:89], v[88:89], v[90:91]
	ds_bpermute_b32 v81, v206, v75
	v_pk_add_f32 v[82:83], v[82:83], v[88:89]
	ds_bpermute_b32 v88, v203, v82
	ds_bpermute_b32 v89, v203, v83
	v_cmp_lt_i32_e32 vcc, v132, v131
	s_waitcnt lgkmcnt(2)
	v_pk_add_f32 v[74:75], v[74:75], v[80:81]
	ds_bpermute_b32 v80, v207, v74
	ds_bpermute_b32 v81, v207, v75
	s_waitcnt lgkmcnt(2)
	v_pk_add_f32 v[82:83], v[82:83], v[88:89]
	ds_bpermute_b32 v88, v204, v82
	ds_bpermute_b32 v89, v204, v83
	v_cndmask_b32_e32 v90, v130, v132, vcc
	v_lshlrev_b32_e32 v208, 2, v90
	s_waitcnt lgkmcnt(2)
	v_pk_add_f32 v[128:129], v[74:75], v[80:81]
	ds_bpermute_b32 v130, v208, v128
	s_waitcnt lgkmcnt(1)
	v_pk_add_f32 v[132:133], v[82:83], v[88:89]
	global_load_dwordx4 v[88:91], v[72:73], off
	global_load_dwordx4 v[80:83], v[72:73], off offset:1024
	s_nop 0
	global_load_dwordx4 v[72:75], v[72:73], off offset:2048
	ds_bpermute_b32 v131, v208, v129
	ds_bpermute_b32 v134, v205, v132
	ds_bpermute_b32 v135, v205, v133
	s_waitcnt vmcnt(15)
	v_mov_b32_e32 v138, v49
	s_waitcnt vmcnt(11)
	v_mov_b32_e32 v139, v33
	s_waitcnt lgkmcnt(2)
	v_pk_add_f32 v[130:131], v[128:129], v[130:131]
	v_mov_b64_e32 v[128:129], s[4:5]
	v_pk_fma_f32 v[130:131], v[130:131], s[2:3], v[128:129] op_sel_hi:[1,0,0]
	s_mov_b32 s3, 0x800000
	v_mul_f32_e32 v136, 0x4b800000, v130
	v_cmp_gt_f32_e64 s[4:5], s3, v130
	v_mov_b32_e32 v137, v32
	v_pk_mul_f32 v[138:139], v[138:139], v[138:139]
	v_cndmask_b32_e64 v130, v130, v136, s[4:5]
	v_mov_b32_e32 v136, v48
	v_mov_b32_e32 v140, v51
	v_mov_b32_e32 v141, v35
	v_pk_fma_f32 v[136:137], v[136:137], v[136:137], v[138:139]
	v_mov_b32_e32 v138, v50
	v_mov_b32_e32 v139, v34
	v_pk_mul_f32 v[140:141], v[140:141], v[140:141]
	s_waitcnt lgkmcnt(0)
	v_pk_add_f32 v[132:133], v[132:133], v[134:135]
	v_pk_fma_f32 v[138:139], v[138:139], v[138:139], v[140:141]
	v_mov_b32_e32 v140, v45
	s_waitcnt vmcnt(10)
	v_mov_b32_e32 v141, v29
	v_pk_add_f32 v[136:137], v[136:137], v[138:139]
	v_mov_b32_e32 v138, v44
	v_mov_b32_e32 v139, v28
	v_pk_mul_f32 v[140:141], v[140:141], v[140:141]
	v_mov_b32_e32 v142, v47
	v_mov_b32_e32 v143, v31
	ds_bpermute_b32 v134, v206, v132
	ds_bpermute_b32 v135, v206, v133
	v_pk_fma_f32 v[138:139], v[138:139], v[138:139], v[140:141]
	v_mov_b32_e32 v140, v46
	v_mov_b32_e32 v141, v30
	v_pk_mul_f32 v[142:143], v[142:143], v[142:143]
	s_waitcnt lgkmcnt(0)
	v_pk_add_f32 v[132:133], v[132:133], v[134:135]
	v_pk_fma_f32 v[140:141], v[140:141], v[140:141], v[142:143]
	v_mov_b32_e32 v142, v43
	v_pk_add_f32 v[138:139], v[138:139], v[140:141]
	v_mov_b32_e32 v140, v41
	s_waitcnt vmcnt(9)
	v_mov_b32_e32 v141, v25
	v_pk_add_f32 v[136:137], v[136:137], v[138:139]
	v_mov_b32_e32 v138, v40
	v_mov_b32_e32 v139, v24
	v_pk_mul_f32 v[140:141], v[140:141], v[140:141]
	v_mov_b32_e32 v143, v27
	v_pk_fma_f32 v[138:139], v[138:139], v[138:139], v[140:141]
	v_mov_b32_e32 v140, v42
	v_mov_b32_e32 v141, v26
	v_pk_mul_f32 v[142:143], v[142:143], v[142:143]
	ds_bpermute_b32 v134, v207, v132
	v_pk_fma_f32 v[140:141], v[140:141], v[140:141], v[142:143]
	ds_bpermute_b32 v135, v207, v133
	v_pk_add_f32 v[138:139], v[138:139], v[140:141]
	v_mov_b32_e32 v140, v37
	s_waitcnt vmcnt(8)
	v_mov_b32_e32 v141, v21
	v_pk_add_f32 v[136:137], v[136:137], v[138:139]
	v_mov_b32_e32 v138, v36
	v_mov_b32_e32 v139, v20
	v_pk_mul_f32 v[140:141], v[140:141], v[140:141]
	v_mov_b32_e32 v142, v39
	v_mov_b32_e32 v143, v23
	v_pk_fma_f32 v[138:139], v[138:139], v[138:139], v[140:141]
	v_mov_b32_e32 v140, v38
	v_mov_b32_e32 v141, v22
	v_pk_mul_f32 v[142:143], v[142:143], v[142:143]
	s_waitcnt lgkmcnt(0)
	v_pk_add_f32 v[132:133], v[132:133], v[134:135]
	v_pk_fma_f32 v[140:141], v[140:141], v[140:141], v[142:143]
	ds_bpermute_b32 v134, v208, v132
	v_pk_add_f32 v[138:139], v[138:139], v[140:141]
	ds_bpermute_b32 v135, v208, v133
	v_pk_add_f32 v[136:137], v[136:137], v[138:139]
	ds_bpermute_b32 v138, v203, v136
	ds_bpermute_b32 v139, v203, v137
	v_mul_f32_e32 v140, 0x4b800000, v131
	v_cmp_gt_f32_e64 s[8:9], s3, v131
	s_waitcnt vmcnt(2)
	v_mov_b32_e32 v141, v89
	s_waitcnt lgkmcnt(2)
	v_pk_add_f32 v[132:133], v[132:133], v[134:135]
	v_cndmask_b32_e64 v131, v131, v140, s[8:9]
	v_mov_b32_e32 v140, v17
	s_waitcnt lgkmcnt(0)
	v_pk_add_f32 v[134:135], v[136:137], v[138:139]
	v_mov_b32_e32 v138, v16
	v_mov_b32_e32 v139, v88
	v_pk_mul_f32 v[140:141], v[140:141], v[140:141]
	v_mov_b32_e32 v142, v19
	v_mov_b32_e32 v143, v91
	v_pk_fma_f32 v[138:139], v[138:139], v[138:139], v[140:141]
	v_mov_b32_e32 v140, v18
	v_mov_b32_e32 v141, v90
	v_pk_mul_f32 v[142:143], v[142:143], v[142:143]
	v_mov_b32_e32 v144, v15
	v_pk_fma_f32 v[140:141], v[140:141], v[140:141], v[142:143]
	v_mov_b32_e32 v142, v13
	s_waitcnt vmcnt(1)
	v_mov_b32_e32 v143, v81
	v_pk_add_f32 v[138:139], v[138:139], v[140:141]
	v_mov_b32_e32 v140, v12
	v_mov_b32_e32 v141, v80
	v_pk_mul_f32 v[142:143], v[142:143], v[142:143]
	v_mov_b32_e32 v145, v83
	v_pk_fma_f32 v[140:141], v[140:141], v[140:141], v[142:143]
	v_mov_b32_e32 v142, v14
	v_mov_b32_e32 v143, v82
	v_pk_mul_f32 v[144:145], v[144:145], v[144:145]
	ds_bpermute_b32 v136, v204, v134
	v_pk_fma_f32 v[142:143], v[142:143], v[142:143], v[144:145]
	v_mov_b32_e32 v144, v11
	v_pk_add_f32 v[140:141], v[140:141], v[142:143]
	v_mov_b32_e32 v142, v9
	s_waitcnt vmcnt(0)
	v_mov_b32_e32 v143, v73
	v_pk_add_f32 v[138:139], v[138:139], v[140:141]
	v_mov_b32_e32 v140, v8
	v_mov_b32_e32 v141, v72
	v_pk_mul_f32 v[142:143], v[142:143], v[142:143]
	v_mov_b32_e32 v145, v75
	v_pk_fma_f32 v[140:141], v[140:141], v[140:141], v[142:143]
	v_mov_b32_e32 v142, v10
	v_mov_b32_e32 v143, v74
	v_pk_mul_f32 v[144:145], v[144:145], v[144:145]
	ds_bpermute_b32 v137, v204, v135
	v_pk_fma_f32 v[142:143], v[142:143], v[142:143], v[144:145]
	v_mov_b32_e32 v144, v7
	v_pk_add_f32 v[140:141], v[140:141], v[142:143]
	v_mov_b32_e32 v142, v5
	v_mov_b32_e32 v143, v1
	v_pk_add_f32 v[138:139], v[138:139], v[140:141]
	v_mov_b32_e32 v140, v4
	v_mov_b32_e32 v141, v0
	v_pk_mul_f32 v[142:143], v[142:143], v[142:143]
	v_mov_b32_e32 v145, v3
	v_pk_fma_f32 v[140:141], v[140:141], v[140:141], v[142:143]
	v_mov_b32_e32 v142, v6
	v_mov_b32_e32 v143, v2
	v_pk_mul_f32 v[144:145], v[144:145], v[144:145]
	s_waitcnt lgkmcnt(0)
	v_pk_add_f32 v[134:135], v[134:135], v[136:137]
	v_pk_fma_f32 v[142:143], v[142:143], v[142:143], v[144:145]
	ds_bpermute_b32 v136, v205, v134
	v_pk_add_f32 v[140:141], v[140:141], v[142:143]
	ds_bpermute_b32 v137, v205, v135
	v_pk_add_f32 v[138:139], v[138:139], v[140:141]
	ds_bpermute_b32 v140, v203, v138
	ds_bpermute_b32 v141, v203, v139
	v_pk_fma_f32 v[132:133], v[132:133], s[2:3], v[128:129] op_sel_hi:[1,0,0]
	s_waitcnt lgkmcnt(2)
	v_pk_add_f32 v[134:135], v[134:135], v[136:137]
	ds_bpermute_b32 v136, v206, v134
	ds_bpermute_b32 v137, v206, v135
	s_waitcnt lgkmcnt(2)
	v_pk_add_f32 v[138:139], v[138:139], v[140:141]
	ds_bpermute_b32 v140, v204, v138
	ds_bpermute_b32 v141, v204, v139
	v_mul_f32_e32 v142, 0x4b800000, v132
	s_waitcnt lgkmcnt(2)
	v_pk_add_f32 v[134:135], v[134:135], v[136:137]
	ds_bpermute_b32 v136, v207, v134
	ds_bpermute_b32 v137, v207, v135
	s_waitcnt lgkmcnt(2)
	v_pk_add_f32 v[138:139], v[138:139], v[140:141]
	ds_bpermute_b32 v140, v205, v138
	ds_bpermute_b32 v141, v205, v139
	v_cmp_gt_f32_e64 s[10:11], s3, v132
	s_waitcnt lgkmcnt(2)
	v_pk_add_f32 v[134:135], v[134:135], v[136:137]
	ds_bpermute_b32 v136, v208, v134
	ds_bpermute_b32 v137, v208, v135
	s_waitcnt lgkmcnt(2)
	v_pk_add_f32 v[138:139], v[138:139], v[140:141]
	ds_bpermute_b32 v140, v206, v138
	ds_bpermute_b32 v141, v206, v139
	s_getreg_b32 s6, hwreg(HW_REG_XCC_ID, 0, 4)
	s_waitcnt lgkmcnt(2)
	v_pk_add_f32 v[134:135], v[134:135], v[136:137]
	s_waitcnt vmcnt(0)
	v_cndmask_b32_e64 v132, v132, v142, s[10:11]
	s_waitcnt lgkmcnt(0)
	v_pk_add_f32 v[138:139], v[138:139], v[140:141]
	ds_bpermute_b32 v140, v207, v138
	ds_bpermute_b32 v141, v207, v139
	v_pk_fma_f32 v[134:135], v[134:135], s[2:3], v[128:129] op_sel_hi:[1,0,0]
	v_mul_f32_e32 v142, 0x4b800000, v133
	v_mul_f32_e32 v136, 0x4b800000, v134
	v_cmp_gt_f32_e64 s[14:15], s3, v134
	s_waitcnt lgkmcnt(0)
	v_pk_add_f32 v[138:139], v[138:139], v[140:141]
	ds_bpermute_b32 v140, v208, v138
	ds_bpermute_b32 v141, v208, v139
	v_cndmask_b32_e64 v136, v134, v136, s[14:15]
	v_mul_f32_e32 v134, 0x4b800000, v135
	v_cmp_gt_f32_e64 s[16:17], s3, v135
	v_cmp_gt_f32_e64 s[12:13], s3, v133
	s_waitcnt lgkmcnt(0)
	v_cndmask_b32_e64 v137, v135, v134, s[16:17]
	v_pk_add_f32 v[134:135], v[138:139], v[140:141]
	v_cndmask_b32_e64 v133, v133, v142, s[12:13]
	v_pk_fma_f32 v[128:129], v[134:135], s[2:3], v[128:129] op_sel_hi:[1,0,0]
	s_barrier
	v_mul_f32_e32 v134, 0x4b800000, v128
	v_cmp_gt_f32_e64 s[18:19], s3, v128
	v_cmp_gt_f32_e64 s[20:21], s3, v129
	s_nop 0
	v_cndmask_b32_e64 v138, v128, v134, s[18:19]
	v_mul_f32_e32 v128, 0x4b800000, v129
	v_cndmask_b32_e64 v139, v129, v128, s[20:21]
	s_mov_b64 s[2:3], exec
	v_readlane_b32 s22, v234, 18
	v_readlane_b32 s23, v234, 19
	s_and_b64 s[22:23], s[2:3], s[22:23]
	s_mov_b64 exec, s[22:23]
	s_cbranch_execz .LBB0_146
	s_add_i32 s7, 0, 0x20000
	v_mov_b32_e32 v128, s7
	s_waitcnt vmcnt(0) expcnt(0) lgkmcnt(0)
	ds_read_b32 v134, v128
	s_add_i32 s7, 0, 0x20004
	v_mov_b32_e32 v128, s7
	ds_read_b32 v128, v128
	s_and_b32 s74, s6, 15
	s_waitcnt lgkmcnt(1)
	v_cmp_ne_u32_e32 vcc, 0, v134
	s_cbranch_vccnz .LBB0_110
	s_load_dwordx2 s[24:25], s[0:1], 0xb0
	s_load_dword s23, s[0:1], 0xb8
	s_add_u32 s6, s78, 0xefe8a00
	s_addc_u32 s7, s79, 0
	s_add_u32 s22, s78, 0xefe8c00
	s_waitcnt lgkmcnt(0)
	s_mul_i32 s75, s25, s24
	s_mul_i32 s75, s75, s23
	s_addc_u32 s23, s79, 0
	s_add_u32 s24, s78, 0xefe8d00
	s_addc_u32 s25, s79, 0
	s_add_u32 s26, s78, 0xefe8e00
	s_addc_u32 s27, s79, 0
	s_add_u32 s28, s78, 0xefe8f00
	s_addc_u32 s29, s79, 0
	s_add_u32 s30, s78, 0xefe9000
	s_addc_u32 s31, s79, 0
	s_add_u32 s34, s78, 0xefe9100
	s_addc_u32 s35, s79, 0
	s_add_u32 s36, s78, 0xefe9200
	s_addc_u32 s37, s79, 0
	s_add_u32 s38, s78, 0xefe9300
	s_addc_u32 s39, s79, 0
	s_add_u32 s40, s78, 0xefe9400
	s_addc_u32 s41, s79, 0
	s_add_u32 s42, s78, 0xefe9500
	s_addc_u32 s43, s79, 0
	s_add_u32 s44, s78, 0xefe9600
	s_addc_u32 s45, s79, 0
	s_add_u32 s46, s78, 0xefe9700
	s_addc_u32 s47, s79, 0
	s_add_u32 s48, s78, 0xefe9800
	s_addc_u32 s49, s79, 0
	s_add_u32 s50, s78, 0xefe9900
	s_addc_u32 s51, s79, 0
	s_add_u32 s52, s78, 0xefe9a00
	s_addc_u32 s53, s79, 0
	s_add_u32 s54, s78, 0xefe9b00
	s_addc_u32 s55, s79, 0
	s_mov_b32 s80, 1
	v_mov_b32_e32 v152, 0
	s_branch .LBB0_98

.LBB0_157:
	s_or_b64 exec, exec, s[2:3]
	s_getpc_b64 s[98:99]
	v_lshlrev_b32_e32 v246, 7, v202
	v_mov_b32_e32 v247, 0
	v_lshl_add_u64 v[246:247], v[246:247], 0, s[98:99]
	global_load_dword v248, v[246:247], off
	s_add_u32 s52, s78, 0xcc0000
	s_addc_u32 s53, s79, 0
	s_cmpk_gt_i32 s96, 0x87
	s_cbranch_scc1 .LBB0_163
	s_load_dwordx16 s[36:51], s[0:1], 0x0
	s_load_dword s18, s[0:1], 0xb0
	v_ashrrev_i32_e32 v145, 31, v144
	v_add_u32_e32 v2, 0xfffffe00, v144
	v_lshlrev_b64 v[0:1], 2, v[144:145]
	s_waitcnt lgkmcnt(0)
	s_mov_b64 s[16:17], s[48:49]
	s_add_u32 s2, s16, 0x2000
	s_addc_u32 s3, s17, 0
	s_movk_i32 s19, 0x1ff
	s_mov_b32 s4, s96
	s_branch .LBB0_160
